# stack+prep-Y-xor16-xor32-reductions-via-v_permlane16_32_swap-instead-of-ds_bpermute
# speedup vs baseline: 1.0017x; 1.0017x over previous
; #define ZERO_ENDS4(A) do { if (!pz) A[1] = (u32x4){0u, 0u, 0u, 0u}; if (!nz) A[2] = (u32x4){0u, 0u, 0u, 0u}; } while (0)
; __device__ __forceinline__ void prep_y(int l, int b, int h, int dir, int c, LAS float* rg, const LAS float* cst, int lane) {
;     PREP_COMMON();
;     const bf16* Wi = (const bf16*)(ws + OFF_WIC) + (size_t)dir * DM * 64;
;     u32x4 cir[2][3];
; #pragma unroll
;     for (int ks = 0; ks < 2; ++ks) { const bf16* q = rawA + 3200 + 64 * dir + 32 * ks + 8 * fq; cir[ks][0] = *(const u32x4*)q; cir[ks][1] = *(const u32x4*)(q + dp); cir[ks][2] = *(const u32x4*)(q + dn); }
;     u32x4 wir[4][2]; u32x2 kr[4][3], rr_[4][3];
; #pragma unroll
;     for (int nb = 0; nb < 4; ++nb) { const int chr = h * 64 + nb * 16 + fr;
; #pragma unroll
;         for (int ks = 0; ks < 2; ++ks) wir[nb][ks] = *(const u32x4*)(Wi + (size_t)chr * 64 + 32 * ks + 8 * fq);
;         const bf16* q = rawA + h * 64 + nb * 16 + 4 * fq;
;         rr_[nb][0] = *(const u32x2*)q; rr_[nb][1] = *(const u32x2*)(q + dp); rr_[nb][2] = *(const u32x2*)(q + dn);
;         kr[nb][0] = *(const u32x2*)(q + 1024); kr[nb][1] = *(const u32x2*)(q + 1024 + dp); kr[nb][2] = *(const u32x2*)(q + 1024 + dn); }
;     __builtin_amdgcn_sched_barrier(0);
;     bf16x8 bi[2];
; #pragma unroll
;     for (int ks = 0; ks < 2; ++ks) {
;         float o[8]; const int cc = 128 + 64 * dir + 32 * ks + 8 * fq;
;         ZERO_ENDS4(cir[ks]);
;         mix8p(cir[ks][0], cir[ks][1], cir[ks][2], cst + C_CMP + cc, cst + C_CMN + cc, o);
.LBB0_370:
	s_cmpk_eq_i32 s81, 0x7f
	s_cbranch_scc1 .LBB0_424
	s_add_i32 s6, s81, 1
	s_lshl_b32 s7, s6, 1
	s_and_b32 s7, s7, 2
	s_or_b32 s7, s7, s87
	s_mulk_i32 s7, 0x4100
	s_add_i32 s82, s7, 0
	s_lshl_b32 s83, s6, 4
	s_mov_b64 s[6:7], -1
	s_and_b64 vcc, exec, s[94:95]
	s_cbranch_vccz .LBB0_375
	s_mov_b64 s[6:7], s[0:1]
	s_load_dwordx2 s[52:53], s[6:7], 0xb8
	v_mov_b32_e32 v144, v160
	s_lshl_b32 s96, s8, 1
	v_and_b32_e32 v145, 15, v144
	v_or_b32_e32 v2, s83, v145
	v_sub_u32_e32 v4, 0x7ff, v2
	v_cndmask_b32_e64 v2, v4, v2, s[38:39]
	v_lshl_add_u64 v[4:5], s[30:31], 0, v[2:3]
	s_waitcnt lgkmcnt(0)
	v_mov_b64_e32 v[10:11], s[52:53]
	v_ashrrev_i32_e32 v46, 4, v144
	v_mad_u64_u32 v[10:11], s[6:7], v4, s22, v[10:11]
	v_mad_i32_i24 v11, v5, s22, v11
	v_lshlrev_b32_e32 v32, 3, v46
	v_lshl_add_u64 v[10:11], v[10:11], 0, s[12:13]
	v_ashrrev_i32_e32 v33, 31, v32
	v_lshl_add_u64 v[20:21], v[10:11], 0, s[96:97]
	v_lshlrev_b64 v[26:27], 1, v[32:33]
	v_lshl_add_u64 v[20:21], v[20:21], 0, v[26:27]
	s_mov_b64 s[6:7], 0x1900
	v_cmp_eq_u32_e32 vcc, 0, v2
	v_cmp_gt_u32_e64 s[48:49], s24, v2
	v_lshl_add_u64 v[40:41], v[20:21], 0, s[6:7]
	v_add_co_u32_e64 v20, s[50:51], s25, v20
	s_add_u32 s6, s52, s5
	v_cndmask_b32_e64 v15, -1, 0, vcc
	v_cndmask_b32_e64 v14, v203, 0, vcc
	v_cndmask_b32_e64 v2, 0, v202, s[48:49]
	v_addc_co_u32_e64 v21, s[50:51], 0, v21, s[50:51]
	s_addc_u32 s7, s53, 0
	v_lshl_add_u64 v[42:43], v[40:41], 0, v[14:15]
	v_lshl_add_u64 v[44:45], v[40:41], 0, v[2:3]
	global_load_dwordx4 v[48:51], v[20:21], off offset:2304
	global_load_dwordx4 v[52:55], v[40:41], off offset:64
	global_load_dwordx4 v[108:111], v[42:43], off
	global_load_dwordx4 v[112:115], v[42:43], off offset:64
	global_load_dwordx4 v[146:149], v[44:45], off
	global_load_dwordx4 v[150:153], v[44:45], off offset:64
	v_lshl_add_u64 v[20:21], s[6:7], 0, v[26:27]
	s_mov_b32 s35, s97
	v_lshlrev_b32_e32 v26, 2, v46
	v_lshl_add_u64 v[10:11], v[10:11], 0, s[34:35]
	v_ashrrev_i32_e32 v27, 31, v26
	v_lshl_add_u64 v[26:27], v[26:27], 1, v[10:11]
	v_or_b32_e32 v10, s56, v145
	v_lshlrev_b32_e32 v10, 7, v10
	v_mov_b32_e32 v11, v3
	v_lshl_add_u64 v[10:11], v[20:21], 0, v[10:11]
	s_mov_b64 s[6:7], 0x1b40000
	v_lshl_add_u64 v[20:21], v[10:11], 0, s[6:7]
	s_mov_b32 s6, 0x1b41000
	v_add_co_u32_e64 v10, s[50:51], s6, v10
	v_lshl_add_u64 v[74:75], v[26:27], 0, v[14:15]
	s_nop 0
	v_addc_co_u32_e64 v11, s[50:51], 0, v11, s[50:51]
	v_lshl_add_u64 v[134:135], v[26:27], 0, v[2:3]
	global_load_dwordx4 v[76:79], v[20:21], off offset:64
	global_load_dwordx4 v[68:71], v[20:21], off offset:2048
	global_load_dwordx2 v[130:131], v[74:75], off
	global_load_dwordx4 v[64:67], v[20:21], off offset:2112
	global_load_dwordx4 v[80:83], v[10:11], off offset:-4096
	global_load_dwordx4 v[60:63], v[10:11], off
	global_load_dwordx4 v[56:59], v[10:11], off offset:64
	global_load_dwordx4 v[44:47], v[10:11], off offset:2048
	global_load_dwordx4 v[40:43], v[10:11], off offset:2112
	global_load_dwordx2 v[116:117], v[26:27], off
	global_load_dwordx2 v[96:97], v[26:27], off offset:32
	global_load_dwordx2 v[86:87], v[26:27], off offset:64
	s_nop 0
	global_load_dwordx2 v[10:11], v[26:27], off offset:96
	global_load_dwordx2 v[138:139], v[74:75], off offset:2048
	global_load_dwordx2 v[98:99], v[74:75], off offset:32
	global_load_dwordx2 v[88:89], v[74:75], off offset:64
	global_load_dwordx2 v[14:15], v[74:75], off offset:96
	global_load_dwordx2 v[142:143], v[134:135], off offset:2048
	global_load_dwordx2 v[100:101], v[134:135], off offset:32
	global_load_dwordx2 v[90:91], v[134:135], off offset:64
	global_load_dwordx2 v[20:21], v[134:135], off offset:96
	global_load_dwordx2 v[72:73], v[26:27], off offset:2048
	global_load_dwordx2 v[102:103], v[26:27], off offset:2080
	global_load_dwordx2 v[92:93], v[26:27], off offset:2112
	s_nop 0
	global_load_dwordx2 v[26:27], v[26:27], off offset:2144
	s_nop 0
	global_load_dwordx2 v[132:133], v[134:135], off
	global_load_dwordx2 v[104:105], v[74:75], off offset:2080
	global_load_dwordx2 v[94:95], v[74:75], off offset:2112
	global_load_dwordx2 v[84:85], v[74:75], off offset:2144
	global_load_dwordx2 v[106:107], v[134:135], off offset:2080
	global_load_dwordx2 v[136:137], v[134:135], off offset:2112
	global_load_dwordx2 v[140:141], v[134:135], off offset:2144
	v_mov_b32_e32 v2, s82
	v_mad_u32_u24 v33, v145, s72, v2
	v_add_u32_e32 v2, s9, v32
	v_lshl_add_u32 v2, v2, 2, 0
	s_waitcnt vmcnt(35)
	v_cndmask_b32_e64 v135, v108, 0, vcc
	v_add_u32_e32 v170, 0x24800, v2
	v_cndmask_b32_e64 v74, v111, 0, vcc
	v_cndmask_b32_e64 v75, v110, 0, vcc
	v_cndmask_b32_e64 v134, v109, 0, vcc
	s_waitcnt vmcnt(33)
	v_cndmask_b32_e64 v145, 0, v149, s[48:49]
	v_cndmask_b32_e64 v158, 0, v148, s[48:49]
	v_cndmask_b32_e64 v159, 0, v147, s[48:49]
	v_cndmask_b32_e64 v168, 0, v146, s[48:49]
	v_add_u32_e32 v2, 0x24c00, v2
	ds_read_b128 v[108:111], v170
	ds_read_b128 v[146:149], v170 offset:16
	ds_read_b128 v[154:157], v2
	ds_read_b128 v[224:227], v2 offset:16
	v_lshlrev_b32_e32 v171, 16, v48
	v_lshlrev_b32_e32 v228, 16, v135
	v_lshlrev_b32_e32 v219, 16, v168
	v_sub_f32_e32 v228, v228, v171
	v_and_b32_e32 v48, 0xffff0000, v48
	v_and_b32_e32 v135, 0xffff0000, v135
	v_sub_f32_e32 v219, v219, v171
	s_waitcnt lgkmcnt(3)
	v_fmac_f32_e32 v171, v108, v228
	v_and_b32_e32 v108, 0xffff0000, v168
	v_sub_f32_e32 v135, v135, v48
	v_sub_f32_e32 v108, v108, v48
	v_fmac_f32_e32 v48, v109, v135
	s_waitcnt lgkmcnt(1)
; __device__ __forceinline__ f32x2 mixp(unsigned c, unsigned pv, unsigned nv, f32x2 m1, f32x2 m2) {
;     const float c0 = bflo(c), c1 = bfhi(c);
;     float r0 = __builtin_fmaf(m2.x, bflo(nv) - c0, __builtin_fmaf(m1.x, bflo(pv) - c0, c0)), r1 = __builtin_fmaf(m2.y, bfhi(nv) - c1, __builtin_fmaf(m1.y, bfhi(pv) - c1, c1));
;     asm("" : "+v"(r0), "+v"(r1));
;     return (f32x2){r0, r1};
; }
; __device__ __forceinline__ void mix8p(const u32x4 c, const u32x4 pv, const u32x4 nv, const LAS float* mp, const LAS float* mn, float* o) {
;     const f32x4 a0 = *(const LAS f32x4*)mp, a1 = *(const LAS f32x4*)(mp + 4), b0 = *(const LAS f32x4*)mn, b1 = *(const LAS f32x4*)(mn + 4);
;     const f32x2 r0 = mixp(c.x, pv.x, nv.x, (f32x2){a0.x, a0.y}, (f32x2){b0.x, b0.y}), r1 = mixp(c.y, pv.y, nv.y, (f32x2){a0.z, a0.w}, (f32x2){b0.z, b0.w});
;     const f32x2 r2 = mixp(c.z, pv.z, nv.z, (f32x2){a1.x, a1.y}, (f32x2){b1.x, b1.y}), r3 = mixp(c.w, pv.w, nv.w, (f32x2){a1.z, a1.w}, (f32x2){b1.z, b1.w});
;     o[0] = r0.x; o[1] = r0.y; o[2] = r1.x; o[3] = r1.y; o[4] = r2.x; o[5] = r2.y; o[6] = r3.x; o[7] = r3.y;
; }
; __device__ __forceinline__ void mix4p(const u32x2 c, const u32x2 pv, const u32x2 nv, const LAS float* mp, const LAS float* mn, float* o) {
;     const f32x4 a0 = *(const LAS f32x4*)mp, b0 = *(const LAS f32x4*)mn;
;     const f32x2 r0 = mixp(c.x, pv.x, nv.x, (f32x2){a0.x, a0.y}, (f32x2){b0.x, b0.y}), r1 = mixp(c.y, pv.y, nv.y, (f32x2){a0.z, a0.w}, (f32x2){b0.z, b0.w});
; __device__ __forceinline__ void prep_y(int l, int b, int h, int dir, int c, LAS float* rg, const LAS float* cst, int lane) {
;     ...
;     bf16x8 bi[2];
; #pragma unroll
;     for (int ks = 0; ks < 2; ++ks) {
;         float o[8]; const int cc = 128 + 64 * dir + 32 * ks + 8 * fq;
;         ZERO_ENDS4(cir[ks]);
;         mix8p(cir[ks][0], cir[ks][1], cir[ks][2], cst + C_CMP + cc, cst + C_CMN + cc, o);
;         bi[ks] = pack8(o);
;     }
;     float kk[16]; float ss = 0.f;
; #pragma unroll
;     for (int nb = 0; nb < 4; ++nb) {
;         const int co = nb * 16 + 4 * fq;
;         ZERO_ENDS2(kr[nb]);
;         mix4p(kr[nb][0], kr[nb][1], kr[nb][2], cst + C_RMP + 64 + co, cst + C_RMN + 64 + co, kk + 4 * nb);
;         const f32x4 kkw = *(const LAS f32x4*)(cst + C_KK + co);
; #pragma unroll
;         for (int i = 0; i < 4; ++i) { const float kr_ = kk[4 * nb + i] * kkw[i]; ss += kr_ * kr_; }
	v_fmac_f32_e32 v48, v155, v108
	v_lshlrev_b32_e32 v108, 16, v49
	v_lshlrev_b32_e32 v135, 16, v134
	v_lshlrev_b32_e32 v109, 16, v159
	v_sub_f32_e32 v135, v135, v108
	v_sub_f32_e32 v109, v109, v108
	v_fmac_f32_e32 v108, v110, v135
	v_and_b32_e32 v49, 0xffff0000, v49
	v_and_b32_e32 v110, 0xffff0000, v134
	v_fmac_f32_e32 v108, v156, v109
	v_and_b32_e32 v109, 0xffff0000, v159
	v_sub_f32_e32 v110, v110, v49
	v_sub_f32_e32 v109, v109, v49
	v_fmac_f32_e32 v49, v111, v110
	v_fmac_f32_e32 v49, v157, v109
	v_lshlrev_b32_e32 v109, 16, v50
	v_lshlrev_b32_e32 v111, 16, v75
	v_lshlrev_b32_e32 v110, 16, v158
	v_sub_f32_e32 v111, v111, v109
	v_sub_f32_e32 v110, v110, v109
	v_fmac_f32_e32 v109, v146, v111
	v_and_b32_e32 v50, 0xffff0000, v50
	v_and_b32_e32 v75, 0xffff0000, v75
	s_waitcnt lgkmcnt(0)
	v_fmac_f32_e32 v109, v224, v110
	v_and_b32_e32 v110, 0xffff0000, v158
	v_sub_f32_e32 v75, v75, v50
	v_sub_f32_e32 v110, v110, v50
	v_fmac_f32_e32 v50, v147, v75
	v_lshlrev_b32_e32 v75, 16, v51
	v_lshlrev_b32_e32 v111, 16, v74
	v_fmac_f32_e32 v50, v225, v110
	v_lshlrev_b32_e32 v110, 16, v145
	v_sub_f32_e32 v111, v111, v75
	v_sub_f32_e32 v110, v110, v75
	v_fmac_f32_e32 v75, v148, v111
	v_and_b32_e32 v51, 0xffff0000, v51
	v_and_b32_e32 v74, 0xffff0000, v74
	v_fmac_f32_e32 v75, v226, v110
	v_and_b32_e32 v110, 0xffff0000, v145
	v_sub_f32_e32 v74, v74, v51
	v_sub_f32_e32 v110, v110, v51
	v_fmac_f32_e32 v51, v149, v74
	v_fmac_f32_e32 v51, v227, v110
	v_cndmask_b32_e64 v135, v112, 0, vcc
	v_fmac_f32_e32 v171, v154, v219
	v_cvt_pk_bf16_f32 v49, v108, v49
	v_cvt_pk_bf16_f32 v50, v109, v50
	v_cvt_pk_bf16_f32 v51, v75, v51
	v_cndmask_b32_e64 v74, v115, 0, vcc
	v_cndmask_b32_e64 v75, v114, 0, vcc
	v_cndmask_b32_e64 v134, v113, 0, vcc
	s_waitcnt vmcnt(32)
	v_cndmask_b32_e64 v145, 0, v153, s[48:49]
	v_cndmask_b32_e64 v154, 0, v152, s[48:49]
	v_cndmask_b32_e64 v155, 0, v151, s[48:49]
	v_cndmask_b32_e64 v156, 0, v150, s[48:49]
	ds_read_b128 v[108:111], v170 offset:128
	ds_read_b128 v[112:115], v170 offset:144
	ds_read_b128 v[146:149], v2 offset:128
	ds_read_b128 v[150:153], v2 offset:144
	v_lshlrev_b32_e32 v2, 16, v52
	v_lshlrev_b32_e32 v158, 16, v135
	v_lshlrev_b32_e32 v157, 16, v156
	v_sub_f32_e32 v158, v158, v2
	v_and_b32_e32 v52, 0xffff0000, v52
	v_and_b32_e32 v135, 0xffff0000, v135
	v_sub_f32_e32 v157, v157, v2
	s_waitcnt lgkmcnt(3)
	v_fmac_f32_e32 v2, v108, v158
	v_and_b32_e32 v108, 0xffff0000, v156
	v_sub_f32_e32 v135, v135, v52
	v_sub_f32_e32 v108, v108, v52
	v_fmac_f32_e32 v52, v109, v135
	s_waitcnt lgkmcnt(1)
	v_fmac_f32_e32 v52, v147, v108
	v_lshlrev_b32_e32 v108, 16, v53
	v_lshlrev_b32_e32 v135, 16, v134
	v_lshlrev_b32_e32 v109, 16, v155
	v_sub_f32_e32 v135, v135, v108
	v_sub_f32_e32 v109, v109, v108
	v_fmac_f32_e32 v108, v110, v135
	v_and_b32_e32 v53, 0xffff0000, v53
	v_and_b32_e32 v110, 0xffff0000, v134
	v_fmac_f32_e32 v108, v148, v109
	v_and_b32_e32 v109, 0xffff0000, v155
	v_sub_f32_e32 v110, v110, v53
	v_sub_f32_e32 v109, v109, v53
	v_fmac_f32_e32 v53, v111, v110
	v_fmac_f32_e32 v53, v149, v109
	v_lshlrev_b32_e32 v109, 16, v54
	v_lshlrev_b32_e32 v111, 16, v75
	v_lshlrev_b32_e32 v110, 16, v154
	v_sub_f32_e32 v111, v111, v109
	v_sub_f32_e32 v110, v110, v109
	v_fmac_f32_e32 v109, v112, v111
	v_and_b32_e32 v54, 0xffff0000, v54
	v_and_b32_e32 v75, 0xffff0000, v75
	s_waitcnt lgkmcnt(0)
	v_fmac_f32_e32 v109, v150, v110
	v_and_b32_e32 v110, 0xffff0000, v154
	v_sub_f32_e32 v75, v75, v54
	v_sub_f32_e32 v110, v110, v54
	v_fmac_f32_e32 v54, v113, v75
	v_lshlrev_b32_e32 v75, 16, v55
	v_lshlrev_b32_e32 v111, 16, v74
	v_fmac_f32_e32 v54, v151, v110
	v_lshlrev_b32_e32 v110, 16, v145
	v_sub_f32_e32 v111, v111, v75
	v_sub_f32_e32 v110, v110, v75
	v_fmac_f32_e32 v75, v114, v111
	v_and_b32_e32 v55, 0xffff0000, v55
	v_and_b32_e32 v74, 0xffff0000, v74
	v_and_b32_e32 v147, -16, v144
	v_fmac_f32_e32 v75, v152, v110
	v_and_b32_e32 v110, 0xffff0000, v145
	v_sub_f32_e32 v74, v74, v55
	v_cvt_pk_bf16_f32 v54, v109, v54
	v_add_u32_e32 v109, 0, v147
	v_sub_f32_e32 v110, v110, v55
	v_fmac_f32_e32 v55, v115, v74
	v_add_u32_e32 v111, 0x25100, v109
	v_fmac_f32_e32 v55, v153, v110
	v_add_u32_e32 v113, 0x25400, v109
	ds_read_b128 v[148:151], v111
	ds_read_b128 v[152:155], v113
	s_waitcnt vmcnt(18)
	v_cndmask_b32_e64 v74, v138, 0, vcc
	v_cvt_pk_bf16_f32 v53, v108, v53
	s_waitcnt vmcnt(14)
	v_cndmask_b32_e64 v108, 0, v142, s[48:49]
	s_waitcnt vmcnt(10)
	v_lshlrev_b32_e32 v110, 16, v72
	v_lshlrev_b32_e32 v114, 16, v74
	v_lshlrev_b32_e32 v112, 16, v108
	v_sub_f32_e32 v114, v114, v110
	v_fmac_f32_e32 v2, v146, v157
	v_sub_f32_e32 v112, v112, v110
	s_waitcnt lgkmcnt(1)
	v_fmac_f32_e32 v110, v148, v114
	s_waitcnt lgkmcnt(0)
	v_fmac_f32_e32 v110, v152, v112
	v_and_b32_e32 v112, 0xffff0000, v72
	v_and_b32_e32 v74, 0xffff0000, v74
	v_cvt_pk_bf16_f32 v52, v2, v52
	v_cndmask_b32_e64 v2, v139, 0, vcc
	v_and_b32_e32 v72, 0xffff0000, v108
	v_sub_f32_e32 v74, v74, v112
	v_cvt_pk_bf16_f32 v55, v75, v55
	v_cndmask_b32_e64 v75, 0, v143, s[48:49]
	v_sub_f32_e32 v72, v72, v112
	v_fmac_f32_e32 v112, v149, v74
	v_lshlrev_b32_e32 v114, 16, v73
	v_lshlrev_b32_e32 v74, 16, v2
	v_fmac_f32_e32 v112, v153, v72
	v_lshlrev_b32_e32 v72, 16, v75
	v_sub_f32_e32 v74, v74, v114
	v_sub_f32_e32 v72, v72, v114
	v_fmac_f32_e32 v114, v150, v74
	v_and_b32_e32 v108, 0xffff0000, v73
	v_and_b32_e32 v2, 0xffff0000, v2
	v_fmac_f32_e32 v114, v154, v72
	v_and_b32_e32 v72, 0xffff0000, v75
	v_sub_f32_e32 v2, v2, v108
	v_sub_f32_e32 v72, v72, v108
	v_fmac_f32_e32 v108, v151, v2
	v_add_u32_e32 v2, 0x25a00, v109
	v_fmac_f32_e32 v108, v155, v72
	ds_read_b128 v[72:75], v2
	ds_read_b128 v[148:151], v111 offset:64
	ds_read_b128 v[152:155], v113 offset:64
	s_waitcnt vmcnt(5)
; #define LAS __attribute__((address_space(3)))
; #define MFMA16(a, b, c) __builtin_amdgcn_mfma_f32_16x16x32_bf16((a), (b), (c), 0, 0, 0)
; #define ZERO_ENDS2(A) do { if (!pz) A[1] = (u32x2){0u, 0u}; if (!nz) A[2] = (u32x2){0u, 0u}; } while (0)
; __device__ __forceinline__ void prep_y(int l, int b, int h, int dir, int c, LAS float* rg, const LAS float* cst, int lane) {
;     ...
;     float kk[16]; float ss = 0.f;
; #pragma unroll
;     for (int nb = 0; nb < 4; ++nb) {
;         const int co = nb * 16 + 4 * fq;
;         ZERO_ENDS2(kr[nb]);
;         mix4p(kr[nb][0], kr[nb][1], kr[nb][2], cst + C_RMP + 64 + co, cst + C_RMN + 64 + co, kk + 4 * nb);
;         const f32x4 kkw = *(const LAS f32x4*)(cst + C_KK + co);
; #pragma unroll
;         for (int i = 0; i < 4; ++i) { const float kr_ = kk[4 * nb + i] * kkw[i]; ss += kr_ * kr_; }
;     }
;     ss += __shfl_xor(ss, 16); ss += __shfl_xor(ss, 32);
;     const float nrm = rsqrtf(ss + 1e-12f);
;     float cs = 0.f;
; #pragma unroll
;     for (int nb = 0; nb < 4; ++nb) {
;         f32x4 aI = {0.f, 0.f, 0.f, 0.f};
; #pragma unroll
;         for (int ks = 0; ks < 2; ++ks) aI = MFMA16(__builtin_bit_cast(bf16x8, wir[nb][ks]), bi[ks], aI);
;         const int co = nb * 16 + 4 * fq;
;         float rr[4];
;         ZERO_ENDS2(rr_[nb]);
;         mix4p(rr_[nb][0], rr_[nb][1], rr_[nb][2], cst + C_RMP + co, cst + C_RMN + co, rr);
;         const f32x4 ibias = *(const LAS f32x4*)(cst + C_IB + 64 * dir + co);
;         const f32x4 kkw = *(const LAS f32x4*)(cst + C_KK + co), kaw = *(const LAS f32x4*)(cst + C_KA + co), rkw = *(const LAS f32x4*)(cst + C_RK + co);
	v_cndmask_b32_e64 v115, v104, 0, vcc
	s_waitcnt vmcnt(2)
	v_cndmask_b32_e64 v134, 0, v106, s[48:49]
	v_lshlrev_b32_e32 v106, 16, v102
	v_lshlrev_b32_e32 v135, 16, v115
	v_lshlrev_b32_e32 v104, 16, v134
	v_sub_f32_e32 v135, v135, v106
	v_sub_f32_e32 v104, v104, v106
	s_waitcnt lgkmcnt(1)
	v_fmac_f32_e32 v106, v148, v135
	s_waitcnt lgkmcnt(0)
	v_fmac_f32_e32 v106, v152, v104
	v_and_b32_e32 v104, 0xffff0000, v102
	v_and_b32_e32 v115, 0xffff0000, v115
	v_and_b32_e32 v102, 0xffff0000, v134
	v_sub_f32_e32 v115, v115, v104
	v_cndmask_b32_e64 v105, v105, 0, vcc
	v_sub_f32_e32 v102, v102, v104
	v_fmac_f32_e32 v104, v149, v115
	v_cndmask_b32_e64 v107, 0, v107, s[48:49]
	v_fmac_f32_e32 v104, v153, v102
	v_lshlrev_b32_e32 v102, 16, v103
	v_lshlrev_b32_e32 v134, 16, v105
	v_and_b32_e32 v103, 0xffff0000, v103
	v_and_b32_e32 v105, 0xffff0000, v105
	v_lshlrev_b32_e32 v115, 16, v107
	v_sub_f32_e32 v134, v134, v102
	v_and_b32_e32 v107, 0xffff0000, v107
	v_sub_f32_e32 v105, v105, v103
	v_sub_f32_e32 v115, v115, v102
	v_fmac_f32_e32 v102, v150, v134
	v_sub_f32_e32 v107, v107, v103
	v_fmac_f32_e32 v103, v151, v105
	ds_read_b128 v[148:151], v2 offset:64
	v_fmac_f32_e32 v102, v154, v115
	v_fmac_f32_e32 v103, v155, v107
	s_waitcnt vmcnt(1)
	v_cndmask_b32_e64 v143, 0, v137, s[48:49]
	s_waitcnt lgkmcnt(0)
	v_mul_f32_e32 v107, v106, v148
	v_mul_f32_e32 v105, v104, v149
	v_pk_mul_f32 v[134:135], v[102:103], v[150:151]
	v_cndmask_b32_e64 v145, 0, v136, s[48:49]
	ds_read_b128 v[136:139], v111 offset:128
	ds_read_b128 v[148:151], v113 offset:128
	v_cndmask_b32_e64 v142, v94, 0, vcc
	v_lshlrev_b32_e32 v94, 16, v92
	v_lshlrev_b32_e32 v146, 16, v142
	v_cndmask_b32_e64 v115, v95, 0, vcc
	v_lshlrev_b32_e32 v95, 16, v145
	v_sub_f32_e32 v146, v146, v94
	v_sub_f32_e32 v95, v95, v94
	s_waitcnt lgkmcnt(1)
	v_fmac_f32_e32 v94, v136, v146
	s_waitcnt lgkmcnt(0)
	v_fmac_f32_e32 v94, v148, v95
	v_and_b32_e32 v95, 0xffff0000, v92
	v_and_b32_e32 v136, 0xffff0000, v142
	v_and_b32_e32 v92, 0xffff0000, v145
	v_sub_f32_e32 v136, v136, v95
	v_sub_f32_e32 v92, v92, v95
	v_fmac_f32_e32 v95, v137, v136
	v_fmac_f32_e32 v95, v149, v92
	v_lshlrev_b32_e32 v92, 16, v93
	v_lshlrev_b32_e32 v137, 16, v115
	v_lshlrev_b32_e32 v136, 16, v143
	v_sub_f32_e32 v137, v137, v92
	v_sub_f32_e32 v136, v136, v92
	v_fmac_f32_e32 v92, v138, v137
	v_and_b32_e32 v93, 0xffff0000, v93
	v_and_b32_e32 v115, 0xffff0000, v115
	v_fmac_f32_e32 v92, v150, v136
	v_and_b32_e32 v136, 0xffff0000, v143
	v_sub_f32_e32 v115, v115, v93
	v_sub_f32_e32 v136, v136, v93
	v_fmac_f32_e32 v93, v139, v115
	v_fmac_f32_e32 v93, v151, v136
	ds_read_b128 v[136:139], v2 offset:128
	s_waitcnt vmcnt(0)
	v_cndmask_b32_e64 v146, 0, v141, s[48:49]
	v_cndmask_b32_e64 v152, 0, v140, s[48:49]
	ds_read_b128 v[140:143], v111 offset:192
	ds_read_b128 v[148:151], v113 offset:192
	v_cndmask_b32_e64 v145, v84, 0, vcc
	v_lshlrev_b32_e32 v84, 16, v26
	v_lshlrev_b32_e32 v111, 16, v145
	v_cndmask_b32_e64 v115, v85, 0, vcc
	v_lshlrev_b32_e32 v85, 16, v152
	v_sub_f32_e32 v111, v111, v84
	v_sub_f32_e32 v85, v85, v84
	s_waitcnt lgkmcnt(1)
	v_fmac_f32_e32 v84, v140, v111
	s_waitcnt lgkmcnt(0)
	v_fmac_f32_e32 v84, v148, v85
	v_and_b32_e32 v85, 0xffff0000, v26
	v_and_b32_e32 v111, 0xffff0000, v145
	v_and_b32_e32 v26, 0xffff0000, v152
	v_sub_f32_e32 v111, v111, v85
	v_sub_f32_e32 v26, v26, v85
	v_fmac_f32_e32 v85, v141, v111
	v_fmac_f32_e32 v85, v149, v26
	v_lshlrev_b32_e32 v26, 16, v27
	v_lshlrev_b32_e32 v113, 16, v115
	v_lshlrev_b32_e32 v111, 16, v146
	v_sub_f32_e32 v113, v113, v26
	v_sub_f32_e32 v111, v111, v26
	v_fmac_f32_e32 v26, v142, v113
	v_and_b32_e32 v27, 0xffff0000, v27
	v_and_b32_e32 v113, 0xffff0000, v115
	v_fmac_f32_e32 v26, v150, v111
	v_and_b32_e32 v111, 0xffff0000, v146
	v_sub_f32_e32 v113, v113, v27
	v_sub_f32_e32 v111, v111, v27
	v_fmac_f32_e32 v27, v143, v113
	v_and_b32_e32 v113, 64, v198
	v_cvt_pk_bf16_f32 v48, v171, v48
	v_fmac_f32_e32 v27, v151, v111
	v_xor_b32_e32 v111, 16, v198
	v_add_u32_e32 v113, 64, v113
	v_cmp_lt_i32_e64 s[50:51], v111, v113
	v_mfma_f32_16x16x32_bf16 v[80:83], v[80:83], v[48:51], 0
	ds_read_b128 v[140:143], v2 offset:192
	v_cndmask_b32_e64 v111, v198, v111, s[50:51]
	v_lshlrev_b32_e32 v146, 2, v111
	v_xor_b32_e32 v111, 32, v198
	v_cmp_lt_i32_e64 s[50:51], v111, v113
	v_mfma_f32_16x16x32_bf16 v[148:151], v[76:79], v[52:55], v[80:83]
	v_cndmask_b32_e64 v113, 0, v132, s[48:49]
	v_cndmask_b32_e64 v111, v198, v111, s[50:51]
	v_lshlrev_b32_e32 v145, 2, v111
	v_add_u32_e32 v82, 0x25000, v109
	v_cndmask_b32_e64 v80, v131, 0, vcc
	v_cndmask_b32_e64 v81, v130, 0, vcc
	v_cndmask_b32_e64 v111, 0, v133, s[48:49]
	v_add_u32_e32 v83, 0x25300, v109
	ds_read_b128 v[76:79], v82
	ds_read_b128 v[130:133], v83
	v_lshlrev_b32_e32 v170, 16, v116
	v_lshlrev_b32_e32 v152, 16, v81
	v_lshlrev_b32_e32 v115, 16, v113
	v_sub_f32_e32 v152, v152, v170
	v_and_b32_e32 v171, 0xffff0000, v116
	v_and_b32_e32 v81, 0xffff0000, v81
	v_sub_f32_e32 v115, v115, v170
	s_waitcnt lgkmcnt(1)
	v_fmac_f32_e32 v170, v76, v152
	v_and_b32_e32 v76, 0xffff0000, v113
	v_sub_f32_e32 v81, v81, v171
	v_sub_f32_e32 v76, v76, v171
	v_fmac_f32_e32 v171, v77, v81
	v_lshlrev_b32_e32 v219, 16, v117
	v_lshlrev_b32_e32 v77, 16, v80
	s_waitcnt lgkmcnt(0)
	v_fmac_f32_e32 v171, v131, v76
	v_lshlrev_b32_e32 v76, 16, v111
	v_sub_f32_e32 v77, v77, v219
	v_sub_f32_e32 v76, v76, v219
	v_fmac_f32_e32 v219, v78, v77
	v_and_b32_e32 v117, 0xffff0000, v117
	v_and_b32_e32 v77, 0xffff0000, v80
	v_fmac_f32_e32 v219, v132, v76
	v_and_b32_e32 v76, 0xffff0000, v111
	v_sub_f32_e32 v77, v77, v117
	v_sub_f32_e32 v76, v76, v117
	v_fmac_f32_e32 v117, v79, v77
	v_add_u32_e32 v116, s68, v147
	v_fmac_f32_e32 v170, v130, v115
	v_fmac_f32_e32 v117, v133, v76
	ds_read_b128 v[130:133], v116
	v_add_u32_e32 v80, 0x25b00, v109
	v_add_u32_e32 v81, 0x25c00, v109
	ds_read_b128 v[152:155], v80
	ds_read_b128 v[76:79], v81
	s_waitcnt lgkmcnt(2)
; #define LAS __attribute__((address_space(3)))
; __device__ __forceinline__ unsigned cvtpk(float lo, float hi) { const f32x2 v = {lo, hi}; const bf16x2_t b = __builtin_convertvector(v, bf16x2_t); return __builtin_bit_cast(unsigned, b); }
; __device__ __forceinline__ float sigm(float x) { return __builtin_amdgcn_rcpf(1.0f + __expf(-x)); }
; #define MFMA16(a, b, c) __builtin_amdgcn_mfma_f32_16x16x32_bf16((a), (b), (c), 0, 0, 0)
; #define ZERO_ENDS2(A) do { if (!pz) A[1] = (u32x2){0u, 0u}; if (!nz) A[2] = (u32x2){0u, 0u}; } while (0)
; __device__ __forceinline__ void prep_y(int l, int b, int h, int dir, int c, LAS float* rg, const LAS float* cst, int lane) {
;     ...
;     ss += __shfl_xor(ss, 16); ss += __shfl_xor(ss, 32);
;     const float nrm = rsqrtf(ss + 1e-12f);
;     float cs = 0.f;
; #pragma unroll
;     for (int nb = 0; nb < 4; ++nb) {
;         f32x4 aI = {0.f, 0.f, 0.f, 0.f};
; #pragma unroll
;         for (int ks = 0; ks < 2; ++ks) aI = MFMA16(__builtin_bit_cast(bf16x8, wir[nb][ks]), bi[ks], aI);
;         const int co = nb * 16 + 4 * fq;
;         float rr[4];
;         ZERO_ENDS2(rr_[nb]);
;         mix4p(rr_[nb][0], rr_[nb][1], rr_[nb][2], cst + C_RMP + co, cst + C_RMN + co, rr);
;         const f32x4 ibias = *(const LAS f32x4*)(cst + C_IB + 64 * dir + co);
;         const f32x4 kkw = *(const LAS f32x4*)(cst + C_KK + co), kaw = *(const LAS f32x4*)(cst + C_KA + co), rkw = *(const LAS f32x4*)(cst + C_RK + co);
;         f32x4 va, vb, vkd, vr;
; #pragma unroll
;         for (int i = 0; i < 4; ++i) {
;             const float al = sigm(ibias[i] + aI[i]);
;             const float kraw = kk[4 * nb + i];
;             const float kn = kraw * kkw[i] * nrm;
;             const float kd = kraw * (1.0f + (al - 1.0f) * kaw[i]);
;             va[i] = -kn; vb[i] = kn * al; vkd[i] = kd; vr[i] = rr[i];
;             cs += rr[i] * kd * rkw[i];
;         }
;         *(LAS u32x4*)(rs_ + 128 + co) = (u32x4){cvtpk(0.25f * vb[0], 0.25f * vkd[0]), cvtpk(0.25f * vb[1], 0.25f * vkd[1]), cvtpk(0.25f * vb[2], 0.25f * vkd[2]), cvtpk(0.25f * vb[3], 0.25f * vkd[3])};
;         *(LAS u32x2*)(rs_ + 192 + (co >> 1)) = (u32x2){cvtpk(va[0], va[1]), cvtpk(va[2], va[3])};
;         *(LAS u32x2*)(rs_ + 224 + (co >> 1)) = (u32x2){cvtpk(vr[0], vr[1]), cvtpk(vr[2], vr[3])};
	v_add_f32_e32 v109, v148, v130
	v_mul_f32_e32 v109, 0xbfb8aa3b, v109
	v_exp_f32_e32 v109, v109
	v_mov_b32_e32 v224, v73
	s_waitcnt lgkmcnt(1)
	v_mov_b32_e32 v73, v152
	v_add_f32_e32 v109, 1.0, v109
	v_rcp_f32_e32 v130, v109
	v_add_f32_e32 v109, v149, v131
	v_mul_f32_e32 v109, 0xbfb8aa3b, v109
	v_exp_f32_e32 v109, v109
	v_add_f32_e32 v111, -1.0, v130
	v_mov_b32_e32 v225, v153
	v_pk_mul_f32 v[152:153], v[110:111], v[72:73]
	v_add_f32_e32 v109, 1.0, v109
	v_rcp_f32_e32 v148, v109
	v_add_f32_e32 v109, v150, v132
	v_mul_f32_e32 v109, 0xbfb8aa3b, v109
	v_exp_f32_e32 v109, v109
	v_add_f32_e32 v113, -1.0, v148
	v_mov_b32_e32 v156, v75
	v_mov_b32_e32 v75, v154
	v_add_f32_e32 v109, 1.0, v109
	v_rcp_f32_e32 v132, v109
	v_add_f32_e32 v109, v151, v133
	v_mul_f32_e32 v109, 0xbfb8aa3b, v109
	v_exp_f32_e32 v109, v109
	v_add_f32_e32 v115, -1.0, v132
	v_pk_mul_f32 v[226:227], v[112:113], v[224:225]
	v_mul_f32_e32 v131, v152, v152
	v_add_f32_e32 v109, 1.0, v109
	v_rcp_f32_e32 v150, v109
	v_mov_b32_e32 v157, v155
	v_pk_mul_f32 v[154:155], v[114:115], v[74:75]
	v_add_f32_e32 v109, -1.0, v150
	v_fmac_f32_e32 v131, v226, v226
	v_pk_mul_f32 v[158:159], v[108:109], v[156:157]
	v_fmac_f32_e32 v131, v154, v154
	v_fmac_f32_e32 v131, v158, v158
	v_fmac_f32_e32 v131, v107, v107
	v_pk_mul_f32 v[134:135], v[134:135], v[134:135]
	v_fmac_f32_e32 v131, v105, v105
	v_add_f32_e32 v105, v134, v131
	v_pk_mul_f32 v[136:137], v[94:95], v[136:137]
	v_add_f32_e32 v105, v135, v105
	v_pk_mul_f32 v[136:137], v[136:137], v[136:137]
	v_pk_fma_f32 v[72:73], v[110:111], v[72:73], s[2:3]
	v_pk_mul_f32 v[138:139], v[92:93], v[138:139]
	v_add_f32_e32 v105, v105, v136
	v_pk_mul_f32 v[138:139], v[138:139], v[138:139]
	v_add_f32_e32 v105, v137, v105
	v_pk_mul_f32 v[140:141], v[84:85], v[140:141]
	v_add_f32_e32 v105, v138, v105
	v_pk_mul_f32 v[140:141], v[140:141], v[140:141]
	v_add_f32_e32 v105, v139, v105
	v_pk_mul_f32 v[142:143], v[26:27], v[142:143]
	v_add_f32_e32 v105, v105, v140
	v_pk_mul_f32 v[142:143], v[142:143], v[142:143]
	v_add_f32_e32 v105, v141, v105
	v_add_f32_e32 v105, v142, v105
	v_add_f32_e32 v105, v143, v105
	v_mov_b32_e32 v107, v105
	v_mov_b32_e32 v131, v110
	v_mov_b32_e32 v149, v112
	v_pk_fma_f32 v[112:113], v[112:113], v[224:225], s[2:3]
	s_waitcnt lgkmcnt(0)
	v_permlane16_swap_b32_e32 v105, v107
	v_add_f32_e32 v105, v105, v107
	v_mov_b32_e32 v107, v105
	v_pk_fma_f32 v[74:75], v[114:115], v[74:75], s[2:3]
	v_mov_b32_e32 v133, v114
	v_mov_b32_e32 v151, v108
	s_waitcnt lgkmcnt(0)
	v_permlane32_swap_b32_e32 v105, v107
	v_add_f32_e32 v105, v105, v107
	v_add_f32_e32 v105, 0x2b8cbccc, v105
	v_cmp_gt_f32_e64 s[50:51], s19, v105
	v_mul_f32_e32 v107, 0x4b800000, v105
	v_mfma_f32_16x16x32_bf16 v[68:71], v[68:71], v[48:51], 0
	v_cndmask_b32_e64 v105, v105, v107, s[50:51]
	v_rsq_f32_e32 v105, v105
	v_cndmask_b32_e64 v14, v14, 0, vcc
	v_mfma_f32_16x16x32_bf16 v[64:67], v[64:67], v[52:55], v[68:71]
	v_cndmask_b32_e64 v20, 0, v20, s[48:49]
	v_mul_f32_e32 v107, 0x45800000, v105
	v_cndmask_b32_e64 v168, v105, v107, s[50:51]
	v_pk_mul_f32 v[134:135], v[152:153], v[168:169]
	v_mfma_f32_16x16x32_bf16 v[60:63], v[60:63], v[48:51], 0
	v_mov_b32_e32 v135, v73
	v_pk_mul_f32 v[110:111], v[130:131], v[134:135]
	v_pk_mul_f32 v[130:131], v[226:227], v[168:169]
	v_mul_f32_e32 v72, v170, v111
	v_mov_b32_e32 v131, v113
	v_pk_mul_f32 v[112:113], v[148:149], v[130:131]
	v_fma_f32 v72, v76, v72, 0
	v_mul_f32_e32 v73, v171, v113
	v_fmac_f32_e32 v72, v77, v73
	v_pk_mul_f32 v[76:77], v[154:155], v[168:169]
	v_xor_b32_e32 v105, 0x80000000, v130
	v_mov_b32_e32 v77, v75
	v_pk_mul_f32 v[114:115], v[132:133], v[76:77]
	v_pk_add_f32 v[130:131], v[76:77], 0 neg_lo:[1,1] neg_hi:[1,1]
	v_pk_mul_f32 v[74:75], v[158:159], v[168:169]
	v_pk_fma_f32 v[76:77], v[108:109], v[156:157], s[2:3]
	v_mul_f32_e32 v73, v219, v115
	v_mov_b32_e32 v75, v77
	v_pk_mul_f32 v[108:109], v[150:151], v[74:75]
	v_fmac_f32_e32 v72, v78, v73
	v_xor_b32_e32 v107, 0x80000000, v74
	v_mul_f32_e32 v73, v117, v109
	v_pk_mul_f32 v[74:75], v[110:111], s[20:21] op_sel_hi:[1,0]
	v_pk_mul_f32 v[76:77], v[112:113], s[20:21] op_sel_hi:[1,0]
	v_fmac_f32_e32 v72, v79, v73
	v_cvt_pk_bf16_f32 v74, v74, v75
	v_cvt_pk_bf16_f32 v75, v76, v77
	v_pk_mul_f32 v[76:77], v[114:115], s[20:21] op_sel_hi:[1,0]
	v_pk_mul_f32 v[78:79], v[108:109], s[20:21] op_sel_hi:[1,0]
	v_add_u32_e32 v73, v33, v147
	v_pk_add_f32 v[132:133], v[134:135], 0 neg_lo:[1,1] neg_hi:[1,1]
	v_cvt_pk_bf16_f32 v76, v76, v77
	v_cvt_pk_bf16_f32 v77, v78, v79
	v_sub_u32_e32 v78, v73, v32
	ds_write_b128 v73, v[74:77] offset:33280
	v_cvt_pk_bf16_f32 v74, v132, v105
	v_cvt_pk_bf16_f32 v75, v130, v107
	v_cvt_pk_bf16_f32 v76, v170, v171
	v_cvt_pk_bf16_f32 v77, v219, v117
	v_add_u32_e32 v78, 0x8000, v78
	ds_write2_b64 v78, v[74:75], v[76:77] offset0:96 offset1:112
	ds_read_b128 v[68:71], v82 offset:64
	ds_read_b128 v[74:77], v83 offset:64
	v_cndmask_b32_e64 v79, v98, 0, vcc
	v_cndmask_b32_e64 v78, v99, 0, vcc
	v_cndmask_b32_e64 v98, 0, v101, s[48:49]
	v_cndmask_b32_e64 v99, 0, v100, s[48:49]
	v_lshlrev_b32_e32 v117, 16, v96
	v_lshlrev_b32_e32 v101, 16, v79
	v_lshlrev_b32_e32 v100, 16, v99
	v_sub_f32_e32 v101, v101, v117
	v_sub_f32_e32 v100, v100, v117
	s_waitcnt lgkmcnt(1)
	v_fmac_f32_e32 v117, v68, v101
	s_waitcnt lgkmcnt(0)
; #define LAS __attribute__((address_space(3)))
; __device__ __forceinline__ unsigned cvtpk(float lo, float hi) { const f32x2 v = {lo, hi}; const bf16x2_t b = __builtin_convertvector(v, bf16x2_t); return __builtin_bit_cast(unsigned, b); }
; __device__ __forceinline__ float sigm(float x) { return __builtin_amdgcn_rcpf(1.0f + __expf(-x)); }
; #define MFMA16(a, b, c) __builtin_amdgcn_mfma_f32_16x16x32_bf16((a), (b), (c), 0, 0, 0)
; #define ZERO_ENDS2(A) do { if (!pz) A[1] = (u32x2){0u, 0u}; if (!nz) A[2] = (u32x2){0u, 0u}; } while (0)
; __device__ __forceinline__ void prep_y(int l, int b, int h, int dir, int c, LAS float* rg, const LAS float* cst, int lane) {
;     ...
;     for (int nb = 0; nb < 4; ++nb) {
;         f32x4 aI = {0.f, 0.f, 0.f, 0.f};
; #pragma unroll
;         for (int ks = 0; ks < 2; ++ks) aI = MFMA16(__builtin_bit_cast(bf16x8, wir[nb][ks]), bi[ks], aI);
;         const int co = nb * 16 + 4 * fq;
;         float rr[4];
;         ZERO_ENDS2(rr_[nb]);
;         mix4p(rr_[nb][0], rr_[nb][1], rr_[nb][2], cst + C_RMP + co, cst + C_RMN + co, rr);
;         const f32x4 ibias = *(const LAS f32x4*)(cst + C_IB + 64 * dir + co);
;         const f32x4 kkw = *(const LAS f32x4*)(cst + C_KK + co), kaw = *(const LAS f32x4*)(cst + C_KA + co), rkw = *(const LAS f32x4*)(cst + C_RK + co);
;         f32x4 va, vb, vkd, vr;
; #pragma unroll
;         for (int i = 0; i < 4; ++i) {
;             const float al = sigm(ibias[i] + aI[i]);
;             const float kraw = kk[4 * nb + i];
;             const float kn = kraw * kkw[i] * nrm;
;             const float kd = kraw * (1.0f + (al - 1.0f) * kaw[i]);
;             va[i] = -kn; vb[i] = kn * al; vkd[i] = kd; vr[i] = rr[i];
;             cs += rr[i] * kd * rkw[i];
;         }
;         *(LAS u32x4*)(rs_ + 128 + co) = (u32x4){cvtpk(0.25f * vb[0], 0.25f * vkd[0]), cvtpk(0.25f * vb[1], 0.25f * vkd[1]), cvtpk(0.25f * vb[2], 0.25f * vkd[2]), cvtpk(0.25f * vb[3], 0.25f * vkd[3])};
;         *(LAS u32x2*)(rs_ + 192 + (co >> 1)) = (u32x2){cvtpk(va[0], va[1]), cvtpk(va[2], va[3])};
;         *(LAS u32x2*)(rs_ + 224 + (co >> 1)) = (u32x2){cvtpk(vr[0], vr[1]), cvtpk(vr[2], vr[3])};
	v_fmac_f32_e32 v117, v74, v100
	v_and_b32_e32 v130, 0xffff0000, v96
	v_and_b32_e32 v74, 0xffff0000, v79
	v_and_b32_e32 v68, 0xffff0000, v99
	v_sub_f32_e32 v74, v74, v130
	v_sub_f32_e32 v68, v68, v130
	v_fmac_f32_e32 v130, v69, v74
	v_lshlrev_b32_e32 v131, 16, v97
	v_lshlrev_b32_e32 v69, 16, v78
	v_fmac_f32_e32 v130, v75, v68
	v_lshlrev_b32_e32 v68, 16, v98
	v_sub_f32_e32 v69, v69, v131
	v_sub_f32_e32 v68, v68, v131
	v_fmac_f32_e32 v131, v70, v69
	v_and_b32_e32 v132, 0xffff0000, v97
	v_and_b32_e32 v69, 0xffff0000, v78
	v_fmac_f32_e32 v131, v76, v68
	v_and_b32_e32 v68, 0xffff0000, v98
	v_sub_f32_e32 v69, v69, v132
	v_sub_f32_e32 v68, v68, v132
	v_fmac_f32_e32 v132, v71, v69
	v_fmac_f32_e32 v132, v77, v68
	ds_read_b128 v[74:77], v116 offset:64
	ds_read_b128 v[96:99], v2 offset:64
	ds_read_b128 v[108:111], v80 offset:64
	ds_read_b128 v[68:71], v81 offset:64
	s_waitcnt lgkmcnt(3)
	v_add_f32_e32 v65, v65, v75
	v_mul_f32_e32 v65, 0xbfb8aa3b, v65
	v_exp_f32_e32 v65, v65
	v_add_f32_e32 v64, v64, v74
	v_mul_f32_e32 v64, 0xbfb8aa3b, v64
	v_exp_f32_e32 v64, v64
	v_add_f32_e32 v65, 1.0, v65
	v_rcp_f32_e32 v74, v65
	v_add_f32_e32 v65, v66, v76
	v_mul_f32_e32 v65, 0xbfb8aa3b, v65
	v_exp_f32_e32 v65, v65
	v_add_f32_e32 v64, 1.0, v64
	v_rcp_f32_e32 v64, v64
	v_add_f32_e32 v105, -1.0, v74
	v_add_f32_e32 v65, 1.0, v65
	v_rcp_f32_e32 v66, v65
	v_add_f32_e32 v65, v67, v77
	v_mul_f32_e32 v65, 0xbfb8aa3b, v65
	v_exp_f32_e32 v65, v65
	v_add_f32_e32 v107, -1.0, v64
	s_waitcnt lgkmcnt(2)
	v_mov_b32_e32 v112, v96
	s_waitcnt lgkmcnt(1)
	v_mov_b32_e32 v113, v108
	v_pk_mul_f32 v[114:115], v[106:107], v[96:97]
	v_mov_b32_e32 v108, v97
	v_add_f32_e32 v65, 1.0, v65
	v_pk_mul_f32 v[114:115], v[168:169], v[114:115]
	v_pk_fma_f32 v[112:113], v[106:107], v[112:113], s[2:3]
	v_pk_mul_f32 v[96:97], v[104:105], v[108:109]
	v_rcp_f32_e32 v76, v65
	v_mov_b32_e32 v115, v113
	v_mov_b32_e32 v65, v106
	v_pk_mul_f32 v[96:97], v[168:169], v[96:97]
	v_pk_fma_f32 v[106:107], v[104:105], v[108:109], s[2:3]
	v_pk_mul_f32 v[64:65], v[114:115], v[64:65]
	v_mov_b32_e32 v97, v107
	v_mov_b32_e32 v75, v104
	v_mul_f32_e32 v67, v117, v65
	v_pk_mul_f32 v[64:65], v[64:65], s[20:21] op_sel_hi:[1,0]
	v_pk_mul_f32 v[74:75], v[96:97], v[74:75]
	s_waitcnt lgkmcnt(0)
	v_fmac_f32_e32 v72, v68, v67
	v_cvt_pk_bf16_f32 v64, v64, v65
	v_mul_f32_e32 v65, v130, v75
	v_fmac_f32_e32 v72, v69, v65
	v_pk_mul_f32 v[68:69], v[74:75], s[20:21] op_sel_hi:[1,0]
	v_add_f32_e32 v79, -1.0, v66
	v_cvt_pk_bf16_f32 v65, v68, v69
	v_mov_b32_e32 v78, v102
	v_mov_b32_e32 v68, v98
	v_mov_b32_e32 v69, v110
	v_pk_mul_f32 v[74:75], v[102:103], v[98:99]
	v_pk_fma_f32 v[68:69], v[78:79], v[68:69], s[2:3]
	v_pk_mul_f32 v[74:75], v[168:169], v[74:75]
	v_add_f32_e32 v101, -1.0, v76
	v_mov_b32_e32 v75, v69
	v_mov_b32_e32 v67, v102
	v_mov_b32_e32 v100, v103
	v_mov_b32_e32 v110, v99
	v_pk_add_f32 v[68:69], v[74:75], 0 neg_lo:[1,1] neg_hi:[1,1]
	v_pk_mul_f32 v[66:67], v[74:75], v[66:67]
	v_pk_mul_f32 v[74:75], v[100:101], v[110:111]
	v_pk_fma_f32 v[78:79], v[100:101], v[110:111], s[2:3]
	v_pk_mul_f32 v[74:75], v[168:169], v[74:75]
	v_mov_b32_e32 v77, v103
	v_mul_f32_e32 v69, v131, v67
	v_mov_b32_e32 v75, v79
	v_fmac_f32_e32 v72, v70, v69
	v_pk_mul_f32 v[66:67], v[66:67], s[20:21] op_sel_hi:[1,0]
	v_xor_b32_e32 v69, 0x80000000, v74
	v_pk_mul_f32 v[74:75], v[74:75], v[76:77]
	v_cvt_pk_bf16_f32 v66, v66, v67
	v_mul_f32_e32 v67, v132, v75
	v_fmac_f32_e32 v72, v71, v67
	v_pk_mul_f32 v[70:71], v[74:75], s[20:21] op_sel_hi:[1,0]
	v_pk_add_f32 v[112:113], v[114:115], 0 neg_lo:[1,1] neg_hi:[1,1]
	v_xor_b32_e32 v105, 0x80000000, v96
	v_cvt_pk_bf16_f32 v67, v70, v71
	ds_write_b128 v73, v[64:67] offset:33344
	v_cvt_pk_bf16_f32 v64, v112, v105
	v_cvt_pk_bf16_f32 v65, v68, v69
	v_add_u32_e32 v32, v32, v33
	ds_write_b64 v32, v[64:65] offset:33568
	v_cvt_pk_bf16_f32 v64, v117, v130
	v_cvt_pk_bf16_f32 v65, v131, v132
	ds_write_b64 v32, v[64:65] offset:33696
	v_mfma_f32_16x16x32_bf16 v[56:59], v[56:59], v[52:55], v[60:63]
	s_nop 2
	ds_read_b128 v[60:63], v82 offset:128
	ds_read_b128 v[64:67], v83 offset:128
	v_cndmask_b32_e64 v68, v88, 0, vcc
	v_cndmask_b32_e64 v70, 0, v90, s[48:49]
	v_lshlrev_b32_e32 v100, 16, v86
	v_lshlrev_b32_e32 v74, 16, v68
	v_lshlrev_b32_e32 v71, 16, v70
	v_sub_f32_e32 v74, v74, v100
	v_sub_f32_e32 v71, v71, v100
	s_waitcnt lgkmcnt(1)
	v_fmac_f32_e32 v100, v60, v74
	s_waitcnt lgkmcnt(0)
	v_fmac_f32_e32 v100, v64, v71
	v_and_b32_e32 v101, 0xffff0000, v86
	v_and_b32_e32 v64, 0xffff0000, v68
	v_cndmask_b32_e64 v33, v89, 0, vcc
	v_and_b32_e32 v60, 0xffff0000, v70
	v_sub_f32_e32 v64, v64, v101
	v_cndmask_b32_e64 v69, 0, v91, s[48:49]
	v_sub_f32_e32 v60, v60, v101
	v_fmac_f32_e32 v101, v61, v64
	v_lshlrev_b32_e32 v102, 16, v87
	v_lshlrev_b32_e32 v61, 16, v33
	v_fmac_f32_e32 v101, v65, v60
	v_lshlrev_b32_e32 v60, 16, v69
	v_sub_f32_e32 v61, v61, v102
	v_sub_f32_e32 v60, v60, v102
	v_fmac_f32_e32 v102, v62, v61
	v_and_b32_e32 v103, 0xffff0000, v87
	v_and_b32_e32 v33, 0xffff0000, v33
	v_fmac_f32_e32 v102, v66, v60
	v_and_b32_e32 v60, 0xffff0000, v69
	v_sub_f32_e32 v33, v33, v103
	v_sub_f32_e32 v60, v60, v103
	v_fmac_f32_e32 v103, v63, v33
	v_fmac_f32_e32 v103, v67, v60
	ds_read_b128 v[64:67], v116 offset:128
	ds_read_b128 v[68:71], v2 offset:128
	ds_read_b128 v[74:77], v80 offset:128
	ds_read_b128 v[60:63], v81 offset:128
	v_mov_b32_e32 v78, v94
	s_waitcnt lgkmcnt(3)
	v_add_f32_e32 v33, v56, v64
	v_mul_f32_e32 v33, 0xbfb8aa3b, v33
	v_exp_f32_e32 v33, v33
	s_waitcnt lgkmcnt(2)
	v_mov_b32_e32 v96, v68
	s_waitcnt lgkmcnt(1)
; #define LAS __attribute__((address_space(3)))
; __device__ __forceinline__ unsigned cvtpk(float lo, float hi) { const f32x2 v = {lo, hi}; const bf16x2_t b = __builtin_convertvector(v, bf16x2_t); return __builtin_bit_cast(unsigned, b); }
; __device__ __forceinline__ float sigm(float x) { return __builtin_amdgcn_rcpf(1.0f + __expf(-x)); }
; #define MFMA16(a, b, c) __builtin_amdgcn_mfma_f32_16x16x32_bf16((a), (b), (c), 0, 0, 0)
; #define ZERO_ENDS2(A) do { if (!pz) A[1] = (u32x2){0u, 0u}; if (!nz) A[2] = (u32x2){0u, 0u}; } while (0)
; __device__ __forceinline__ void prep_y(int l, int b, int h, int dir, int c, LAS float* rg, const LAS float* cst, int lane) {
;     ...
;     for (int nb = 0; nb < 4; ++nb) {
;         f32x4 aI = {0.f, 0.f, 0.f, 0.f};
; #pragma unroll
;         for (int ks = 0; ks < 2; ++ks) aI = MFMA16(__builtin_bit_cast(bf16x8, wir[nb][ks]), bi[ks], aI);
;         const int co = nb * 16 + 4 * fq;
;         float rr[4];
;         ZERO_ENDS2(rr_[nb]);
;         mix4p(rr_[nb][0], rr_[nb][1], rr_[nb][2], cst + C_RMP + co, cst + C_RMN + co, rr);
;         const f32x4 ibias = *(const LAS f32x4*)(cst + C_IB + 64 * dir + co);
;         const f32x4 kkw = *(const LAS f32x4*)(cst + C_KK + co), kaw = *(const LAS f32x4*)(cst + C_KA + co), rkw = *(const LAS f32x4*)(cst + C_RK + co);
;         f32x4 va, vb, vkd, vr;
; #pragma unroll
;         for (int i = 0; i < 4; ++i) {
;             const float al = sigm(ibias[i] + aI[i]);
;             const float kraw = kk[4 * nb + i];
;             const float kn = kraw * kkw[i] * nrm;
;             const float kd = kraw * (1.0f + (al - 1.0f) * kaw[i]);
;             va[i] = -kn; vb[i] = kn * al; vkd[i] = kd; vr[i] = rr[i];
;             cs += rr[i] * kd * rkw[i];
;         }
;         *(LAS u32x4*)(rs_ + 128 + co) = (u32x4){cvtpk(0.25f * vb[0], 0.25f * vkd[0]), cvtpk(0.25f * vb[1], 0.25f * vkd[1]), cvtpk(0.25f * vb[2], 0.25f * vkd[2]), cvtpk(0.25f * vb[3], 0.25f * vkd[3])};
;         *(LAS u32x2*)(rs_ + 192 + (co >> 1)) = (u32x2){cvtpk(va[0], va[1]), cvtpk(va[2], va[3])};
;         *(LAS u32x2*)(rs_ + 224 + (co >> 1)) = (u32x2){cvtpk(vr[0], vr[1]), cvtpk(vr[2], vr[3])};
	v_mov_b32_e32 v97, v74
	v_pk_mul_f32 v[98:99], v[94:95], v[68:69]
	v_add_f32_e32 v33, 1.0, v33
	v_rcp_f32_e32 v56, v33
	v_add_f32_e32 v33, v57, v65
	v_mul_f32_e32 v33, 0xbfb8aa3b, v33
	v_exp_f32_e32 v33, v33
	v_add_f32_e32 v79, -1.0, v56
	v_mov_b32_e32 v86, v95
	v_mov_b32_e32 v74, v69
	v_add_f32_e32 v33, 1.0, v33
	v_rcp_f32_e32 v64, v33
	v_add_f32_e32 v33, v58, v66
	v_mul_f32_e32 v33, 0xbfb8aa3b, v33
	v_exp_f32_e32 v33, v33
	v_add_f32_e32 v87, -1.0, v64
	v_pk_mul_f32 v[98:99], v[168:169], v[98:99]
	v_pk_fma_f32 v[78:79], v[78:79], v[96:97], s[2:3]
	v_add_f32_e32 v33, 1.0, v33
	v_rcp_f32_e32 v58, v33
	v_add_f32_e32 v33, v59, v67
	v_mul_f32_e32 v33, 0xbfb8aa3b, v33
	v_exp_f32_e32 v33, v33
	v_pk_mul_f32 v[68:69], v[86:87], v[74:75]
	v_mov_b32_e32 v99, v79
	v_mov_b32_e32 v57, v94
	v_pk_mul_f32 v[68:69], v[168:169], v[68:69]
	v_pk_fma_f32 v[74:75], v[86:87], v[74:75], s[2:3]
	v_add_f32_e32 v33, 1.0, v33
	v_pk_mul_f32 v[56:57], v[98:99], v[56:57]
	v_mov_b32_e32 v69, v75
	v_mov_b32_e32 v65, v95
	v_rcp_f32_e32 v66, v33
	v_mul_f32_e32 v33, v100, v57
	v_pk_mul_f32 v[56:57], v[56:57], s[20:21] op_sel_hi:[1,0]
	v_pk_mul_f32 v[64:65], v[68:69], v[64:65]
	s_waitcnt lgkmcnt(0)
	v_fmac_f32_e32 v72, v60, v33
	v_cvt_pk_bf16_f32 v56, v56, v57
	v_mul_f32_e32 v57, v101, v65
	v_fmac_f32_e32 v72, v61, v57
	v_pk_mul_f32 v[60:61], v[64:65], s[20:21] op_sel_hi:[1,0]
	v_add_f32_e32 v89, -1.0, v58
	v_cvt_pk_bf16_f32 v57, v60, v61
	v_mov_b32_e32 v88, v92
	v_mov_b32_e32 v60, v70
	v_mov_b32_e32 v61, v76
	v_pk_mul_f32 v[64:65], v[92:93], v[70:71]
	v_pk_fma_f32 v[60:61], v[88:89], v[60:61], s[2:3]
	v_pk_mul_f32 v[64:65], v[168:169], v[64:65]
	v_add_f32_e32 v91, -1.0, v66
	v_mov_b32_e32 v65, v61
	v_mov_b32_e32 v59, v92
	v_mov_b32_e32 v90, v93
	v_mov_b32_e32 v76, v71
	v_pk_add_f32 v[60:61], v[64:65], 0 neg_lo:[1,1] neg_hi:[1,1]
	v_pk_mul_f32 v[58:59], v[64:65], v[58:59]
	v_pk_mul_f32 v[64:65], v[90:91], v[76:77]
	v_xor_b32_e32 v33, 0x80000000, v68
	v_pk_mul_f32 v[64:65], v[168:169], v[64:65]
	v_pk_fma_f32 v[68:69], v[90:91], v[76:77], s[2:3]
	v_mov_b32_e32 v67, v93
	v_mul_f32_e32 v61, v102, v59
	v_mov_b32_e32 v65, v69
	v_fmac_f32_e32 v72, v62, v61
	v_pk_mul_f32 v[58:59], v[58:59], s[20:21] op_sel_hi:[1,0]
	v_xor_b32_e32 v61, 0x80000000, v64
	v_pk_mul_f32 v[64:65], v[64:65], v[66:67]
	v_cvt_pk_bf16_f32 v58, v58, v59
	v_mul_f32_e32 v59, v103, v65
	v_fmac_f32_e32 v72, v63, v59
	v_pk_mul_f32 v[62:63], v[64:65], s[20:21] op_sel_hi:[1,0]
	v_pk_add_f32 v[78:79], v[98:99], 0 neg_lo:[1,1] neg_hi:[1,1]
	v_cvt_pk_bf16_f32 v59, v62, v63
	v_mfma_f32_16x16x32_bf16 v[44:47], v[44:47], v[48:51], 0
	ds_write_b128 v73, v[56:59] offset:33408
	v_cvt_pk_bf16_f32 v56, v78, v33
	v_cvt_pk_bf16_f32 v57, v60, v61
	ds_write_b64 v32, v[56:57] offset:33600
	v_cvt_pk_bf16_f32 v56, v100, v101
	v_cvt_pk_bf16_f32 v57, v102, v103
	ds_write_b64 v32, v[56:57] offset:33728
	v_mfma_f32_16x16x32_bf16 v[40:43], v[40:43], v[52:55], v[44:47]
	s_nop 2
	ds_read_b128 v[44:47], v82 offset:192
	ds_read_b128 v[48:51], v83 offset:192
	v_lshlrev_b32_e32 v53, 16, v14
	v_and_b32_e32 v66, 0xffff0000, v10
	v_and_b32_e32 v14, 0xffff0000, v14
	v_cndmask_b32_e64 v15, v15, 0, vcc
	v_lshlrev_b32_e32 v33, 16, v10
	v_and_b32_e32 v10, 0xffff0000, v20
	v_sub_f32_e32 v14, v14, v66
	v_cndmask_b32_e64 v21, 0, v21, s[48:49]
	v_sub_f32_e32 v10, v10, v66
	s_waitcnt lgkmcnt(1)
	v_fmac_f32_e32 v66, v45, v14
	v_lshlrev_b32_e32 v67, 16, v11
	v_lshlrev_b32_e32 v14, 16, v15
	s_waitcnt lgkmcnt(0)
	v_fmac_f32_e32 v66, v49, v10
	v_lshlrev_b32_e32 v10, 16, v21
	v_sub_f32_e32 v14, v14, v67
	v_sub_f32_e32 v10, v10, v67
	v_fmac_f32_e32 v67, v46, v14
	v_and_b32_e32 v68, 0xffff0000, v11
	v_and_b32_e32 v11, 0xffff0000, v15
	v_lshlrev_b32_e32 v52, 16, v20
	v_sub_f32_e32 v53, v53, v33
	v_fmac_f32_e32 v67, v50, v10
	v_and_b32_e32 v10, 0xffff0000, v21
	v_sub_f32_e32 v11, v11, v68
	v_sub_f32_e32 v52, v52, v33
	v_fmac_f32_e32 v33, v44, v53
	v_sub_f32_e32 v10, v10, v68
	v_fmac_f32_e32 v68, v47, v11
	v_fmac_f32_e32 v33, v48, v52
	v_fmac_f32_e32 v68, v51, v10
	ds_read_b128 v[48:51], v116 offset:192
	ds_read_b128 v[52:55], v2 offset:192
	ds_read_b128 v[56:59], v80 offset:192
	ds_read_b128 v[44:47], v81 offset:192
	v_mov_b32_e32 v14, v84
	s_waitcnt lgkmcnt(3)
; #define LAS __attribute__((address_space(3)))
; __device__ __forceinline__ unsigned cvtpk(float lo, float hi) { const f32x2 v = {lo, hi}; const bf16x2_t b = __builtin_convertvector(v, bf16x2_t); return __builtin_bit_cast(unsigned, b); }
; __device__ __forceinline__ float sigm(float x) { return __builtin_amdgcn_rcpf(1.0f + __expf(-x)); }
; __device__ __forceinline__ void prep_y(int l, int b, int h, int dir, int c, LAS float* rg, const LAS float* cst, int lane) {
;     ...
;         f32x4 va, vb, vkd, vr;
; #pragma unroll
;         for (int i = 0; i < 4; ++i) {
;             const float al = sigm(ibias[i] + aI[i]);
;             const float kraw = kk[4 * nb + i];
;             const float kn = kraw * kkw[i] * nrm;
;             const float kd = kraw * (1.0f + (al - 1.0f) * kaw[i]);
;             va[i] = -kn; vb[i] = kn * al; vkd[i] = kd; vr[i] = rr[i];
;             cs += rr[i] * kd * rkw[i];
;         }
;         *(LAS u32x4*)(rs_ + 128 + co) = (u32x4){cvtpk(0.25f * vb[0], 0.25f * vkd[0]), cvtpk(0.25f * vb[1], 0.25f * vkd[1]), cvtpk(0.25f * vb[2], 0.25f * vkd[2]), cvtpk(0.25f * vb[3], 0.25f * vkd[3])};
;         *(LAS u32x2*)(rs_ + 192 + (co >> 1)) = (u32x2){cvtpk(va[0], va[1]), cvtpk(va[2], va[3])};
;         *(LAS u32x2*)(rs_ + 224 + (co >> 1)) = (u32x2){cvtpk(vr[0], vr[1]), cvtpk(vr[2], vr[3])};
;     }
;     cs += __shfl_xor(cs, 16); cs += __shfl_xor(cs, 32);
;     if (fq == 0) ((float*)(ws + OFF_COEF))[((size_t)dir * T + row) * 16 + h] = cs;
	v_add_f32_e32 v2, v40, v48
	v_mul_f32_e32 v2, 0xbfb8aa3b, v2
	v_exp_f32_e32 v2, v2
	s_waitcnt lgkmcnt(2)
	v_mov_b32_e32 v40, v52
	v_pk_mul_f32 v[64:65], v[84:85], v[52:53]
	v_mov_b32_e32 v11, v84
	v_add_f32_e32 v2, 1.0, v2
	v_rcp_f32_e32 v10, v2
	v_add_f32_e32 v2, v41, v49
	v_mul_f32_e32 v2, 0xbfb8aa3b, v2
	v_exp_f32_e32 v2, v2
	v_add_f32_e32 v15, -1.0, v10
	s_waitcnt lgkmcnt(1)
	v_mov_b32_e32 v41, v56
	v_pk_mul_f32 v[64:65], v[168:169], v[64:65]
	v_add_f32_e32 v2, 1.0, v2
	v_rcp_f32_e32 v20, v2
	v_add_f32_e32 v2, v42, v50
	v_mul_f32_e32 v2, 0xbfb8aa3b, v2
	v_exp_f32_e32 v2, v2
	v_pk_fma_f32 v[14:15], v[14:15], v[40:41], s[2:3]
	v_add_f32_e32 v49, -1.0, v20
	v_add_f32_e32 v2, 1.0, v2
	v_rcp_f32_e32 v42, v2
	v_add_f32_e32 v2, v43, v51
	v_mul_f32_e32 v2, 0xbfb8aa3b, v2
	v_exp_f32_e32 v2, v2
	v_mov_b32_e32 v65, v15
	v_pk_mul_f32 v[10:11], v[64:65], v[10:11]
	v_mov_b32_e32 v48, v85
	v_add_f32_e32 v2, 1.0, v2
	v_rcp_f32_e32 v50, v2
	v_mul_f32_e32 v2, v33, v11
	v_pk_mul_f32 v[10:11], v[10:11], s[20:21] op_sel_hi:[1,0]
	v_mov_b32_e32 v56, v53
	v_cvt_pk_bf16_f32 v40, v10, v11
	v_pk_mul_f32 v[10:11], v[48:49], v[56:57]
	v_pk_fma_f32 v[48:49], v[48:49], v[56:57], s[2:3]
	v_pk_mul_f32 v[10:11], v[168:169], v[10:11]
	v_mov_b32_e32 v21, v85
	v_mov_b32_e32 v11, v49
	v_pk_add_f32 v[14:15], v[64:65], 0 neg_lo:[1,1] neg_hi:[1,1]
	s_waitcnt lgkmcnt(0)
	v_fmac_f32_e32 v72, v44, v2
	v_xor_b32_e32 v2, 0x80000000, v10
	v_pk_mul_f32 v[10:11], v[10:11], v[20:21]
	v_add_f32_e32 v61, -1.0, v42
	v_mul_f32_e32 v15, v66, v11
	v_pk_mul_f32 v[10:11], v[10:11], s[20:21] op_sel_hi:[1,0]
	v_mov_b32_e32 v60, v26
	v_cvt_pk_bf16_f32 v41, v10, v11
	v_mov_b32_e32 v10, v54
	v_mov_b32_e32 v11, v58
	v_pk_mul_f32 v[20:21], v[26:27], v[54:55]
	v_pk_fma_f32 v[10:11], v[60:61], v[10:11], s[2:3]
	v_pk_mul_f32 v[20:21], v[168:169], v[20:21]
	v_mov_b32_e32 v43, v26
	v_mov_b32_e32 v21, v11
	v_pk_add_f32 v[10:11], v[20:21], 0 neg_lo:[1,1] neg_hi:[1,1]
	v_pk_mul_f32 v[20:21], v[20:21], v[42:43]
	v_add_f32_e32 v63, -1.0, v50
	v_mul_f32_e32 v11, v67, v21
	v_pk_mul_f32 v[20:21], v[20:21], s[20:21] op_sel_hi:[1,0]
	v_mov_b32_e32 v62, v27
	v_mov_b32_e32 v58, v55
	v_cvt_pk_bf16_f32 v42, v20, v21
	v_pk_mul_f32 v[20:21], v[62:63], v[58:59]
	v_fmac_f32_e32 v72, v45, v15
	v_pk_mul_f32 v[20:21], v[168:169], v[20:21]
	v_pk_fma_f32 v[44:45], v[62:63], v[58:59], s[2:3]
	v_mov_b32_e32 v51, v27
	v_mov_b32_e32 v21, v45
	v_fmac_f32_e32 v72, v46, v11
	v_xor_b32_e32 v11, 0x80000000, v20
	v_pk_mul_f32 v[20:21], v[20:21], v[50:51]
	v_cvt_pk_bf16_f32 v14, v14, v2
	v_mul_f32_e32 v15, v68, v21
	v_fmac_f32_e32 v72, v47, v15
	v_mov_b32_e32 v2, v72
	v_mov_b32_e32 v196, v72
	v_pk_mul_f32 v[20:21], v[20:21], s[20:21] op_sel_hi:[1,0]
	v_cvt_pk_bf16_f32 v15, v10, v11
	v_cvt_pk_bf16_f32 v43, v20, v21
	v_cvt_pk_bf16_f32 v10, v33, v66
	v_cvt_pk_bf16_f32 v11, v67, v68
	s_waitcnt lgkmcnt(0)
	v_permlane16_swap_b32_e32 v2, v196
	v_add_f32_e32 v2, v196, v2
	ds_write_b128 v73, v[40:43] offset:33472
	ds_write_b64 v32, v[10:11] offset:33760
	v_mov_b32_e32 v196, v2
	s_nop 1
	v_permlane32_swap_b32_e32 v2, v196
	v_cmp_gt_u32_e32 vcc, 16, v144
	ds_write_b64 v32, v[14:15] offset:33632
	s_and_saveexec_b64 s[6:7], vcc
	s_cbranch_execz .LBB0_374
	v_readlane_b32 s35, v255, 56
	s_add_u32 s48, s52, s35
	s_addc_u32 s49, s53, 0
	v_lshlrev_b64 v[4:5], 6, v[4:5]
	v_lshl_add_u64 v[4:5], s[48:49], 0, v[4:5]
	s_mov_b32 s91, s97
	v_lshl_add_u64 v[4:5], v[4:5], 0, s[90:91]
	v_add_co_u32_e32 v4, vcc, 0xdd00000, v4
	s_waitcnt lgkmcnt(1)
	v_add_f32_e32 v2, v2, v196
	v_addc_co_u32_e32 v5, vcc, 0, v5, vcc
	global_store_dword v[4:5], v2, off
